# phase C S5 items: next item's six head loads prefetched into a register bank during the current item; next item starts from the bank
# speedup vs baseline: 1.0084x; 1.0022x over previous
; template <bool OUT>
; DI void s5_item(int wv0, PP p, int item, unsigned char* smem) {
;   const int tid = my_tid(wv0), lane = tid & 63, fr = lane & 15, fq = lane >> 4;
;   const int b = item >> 9, g = (item >> 4) & 31, c8 = item & 15, ch = c8 * 8 + wv0;
;   u16* sBb = (u16*)smem;
;   u16* sCm = sBb + 128 * 16;
;   float* sBU = (float*)(smem + 8192) + wv0 * (16 * 132);
;   u16* sH = (u16*)(smem + 8192 + 8 * 16 * 132 * 4) + wv0 * (16 * 136);
;   *(uint4*)(smem + tid * 16) = *(const uint4*)(p->ws + OFF_S5T + (size_t)g * 8192 + tid * 16);
;   const float2 lb = ((const float2*)(p->ws + OFF_S5L))[g * 64 + lane];
;   const float lbr = lb.x, lbi = lb.y;
;   float2* HL = (float2*)(p->ws + OFF_HLOC) + ((size_t)(b * 128 + ch) * 32 + g) * 64 + lane;
;   float hr = 0.f, hi = 0.f;
;   if (OUT) { const float2 h0 = *HL; hr = h0.x; hi = h0.y; }
;   const u16* U = (const u16*)(p->ws + OFF_U) + ((size_t)(b * S_ + ch * 64)) * 512 + g * 16;
;   u16* YS = (u16*)(p->ws + OFF_YS) + ((size_t)(b * S_ + ch * 64)) * 512 + g * 16;
;   const float dk = p->dsk[g * 16 + fr];
;   const bf16x8 zero8 = {0, 0, 0, 0, 0, 0, 0, 0};
;   bf16x8 uall[4];
;   u16 usk[4][4];
; #pragma unroll
;   for (int sub = 0; sub < 4; ++sub) {
;     uall[sub] = fq < 2 ? *(const bf16x8*)(U + (size_t)(sub * 16 + fr) * 512 + 8 * fq) : zero8;
;     if (OUT) {
; #pragma unroll
;       for (int j = 0; j < 4; ++j) usk[sub][j] = U[(size_t)(sub * 16 + 4 * fq + j) * 512 + fr];
;     }
;   }
.LBB0_410:
	s_cmpk_gt_i32 s94, 0x97f
	s_cbranch_scc1 .LBB0_464
	s_mul_i32 s0, s89, 0x2100
	s_and_b32 s2, s82, 0xffffffc0
	s_add_i32 s0, s0, 32
	s_lshr_b32 s3, s82, 8
	s_cmp_eq_u32 s3, 1
	s_cselect_b64 s[8:9], -1, 0
	s_lshl_b32 s1, s89, 12
	s_and_b32 s14, s1, 0x3000
	s_lshl_b32 s1, s3, 6
	s_or_b32 s33, s1, 16
	s_or_b32 s46, s1, 32
	s_or_b32 s47, s1, 48
	s_lshl_b32 s3, s3, 13
	s_lshl_b32 s15, s33, 7
	s_lshl_b32 s16, s46, 7
	s_lshl_b32 s17, s47, 7
	s_cmpk_lt_u32 s82, 0x100
	s_cselect_b64 s[10:11], -1, 0
	s_lshl_b32 s12, s89, 4
	s_and_b32 s48, s12, 0x3fffffc0
	s_lshl_b32 s12, s89, 5
	s_and_b32 s49, s12, 0x60
	s_add_u32 s12, s90, 0xd8
	v_mbcnt_lo_u32_b32 v0, -1, 0
	s_addc_u32 s13, s91, 0
	s_add_i32 s57, s14, 32
	v_mbcnt_hi_u32_b32 v143, -1, v0
	s_add_i32 s50, s57, 0x10000
	s_add_i32 s51, s3, 32
	s_add_i32 s52, s15, 32
	s_add_i32 s53, s16, 32
	s_add_i32 s54, s17, 32
	s_add_i32 s55, s57, 0x14000
	s_add_i32 s56, s57, 0x18000
	s_add_i32 s57, s57, 0x1c000
	s_add_i32 s58, s0, 0x2000
	s_mov_b32 s15, 0
	s_mov_b32 s59, 0x1e3d4000
	v_mov_b32_e32 v129, 0
	s_mov_b32 s60, 0x1e414000
	s_mov_b64 s[16:17], 0x163d4100
	s_mov_b32 s61, 0x133d4100
	s_mov_b32 s62, 0x800000
	s_mov_b64 s[18:19], 0x80000
	s_mov_b64 s[20:21], 0x40000
	s_mov_b64 s[22:23], 0x80
	s_mov_b64 s[24:25], 0x80080
	s_mov_b64 s[26:27], 0x40080
	s_mov_b64 s[28:29], 0x100
	s_mov_b64 s[30:31], 0x80100
	s_mov_b64 s[34:35], 0x40100
	s_mov_b64 s[36:37], 0x180
	s_mov_b64 s[38:39], 0x80180
	s_mov_b64 s[40:41], 0x40380
	s_mov_b32 s63, 0x143d4100
	v_mov_b32_e32 v142, 0x1fd0000
	v_add_u32_e32 v144, s2, v143
	v_mov_b32_e32 v145, 1
	s_mov_b32 s64, s94
	s_mov_b32 s78, -1
	s_branch .LBB0_414
.Lmy_cpf_use:
	s_waitcnt vmcnt(0)
	v_mov_b32_e32 v52, v144
	s_load_dwordx2 s[42:43], s[6:7], 0xc8
	s_add_i32 s2, s64, 0xffffff80
	s_lshr_b32 s66, s2, 9
	s_bfe_u32 s65, s2, 0x50004
	s_lshl_b32 s2, s2, 3
	s_and_b32 s67, s2, 0x78
	s_add_i32 s67, s67, s89
	s_lshl_b32 s2, s65, 13
	s_waitcnt lgkmcnt(0)
	s_add_u32 s2, s42, s2
	v_lshlrev_b32_e32 v4, 4, v52
	v_and_b32_e32 v49, 63, v52
	s_addc_u32 s3, s43, 0
	v_ashrrev_i32_e32 v5, 31, v4
	v_lshl_add_u64 v[0:1], s[2:3], 0, v[4:5]
	v_lshlrev_b32_e32 v48, 3, v49
	v_add_co_u32_e32 v0, vcc, s59, v0
	v_lshl_or_b32 v128, s65, 9, v48
	s_nop 0
	v_addc_co_u32_e32 v1, vcc, 0, v1, vcc
	v_lshl_add_u64 v[6:7], s[42:43], 0, v[128:129]
	v_add_co_u32_e32 v6, vcc, s60, v6
	v_mov_b32_e32 v200, v210
	v_mov_b32_e32 v201, v211
	v_mov_b32_e32 v202, v212
	v_mov_b32_e32 v203, v213
	s_nop 0
	v_addc_co_u32_e32 v7, vcc, 0, v7, vcc
	v_mov_b32_e32 v50, v214
	v_mov_b32_e32 v51, v215
	s_lshl_b32 s14, s66, 13
	s_lshl_b32 s44, s67, 6
	s_add_i32 s14, s44, s14
	s_lshl_b64 s[44:45], s[14:15], 10
	s_add_u32 s14, s42, s44
	s_addc_u32 s45, s43, s45
	s_lshl_b32 s44, s65, 5
	s_add_u32 s44, s14, s44
	v_and_b32_e32 v53, 15, v52
	v_and_b32_e32 v128, 48, v52
	s_addc_u32 s45, s45, 0
	v_add_u32_e32 v204, 32, v4
	v_lshlrev_b32_e32 v4, 9, v53
	v_lshl_add_u64 v[6:7], s[44:45], 0, v[128:129]
	v_mov_b32_e32 v28, 0
	v_mov_b32_e32 v44, 0
	v_mov_b32_e32 v45, 0
	v_mov_b32_e32 v46, 0
	v_cmp_gt_u32_e64 s[2:3], 32, v49
	v_lshlrev_b32_e32 v4, 1, v4
	v_lshl_add_u64 v[6:7], v[6:7], 0, s[16:17]
	v_mov_b32_e32 v47, 0
	s_and_saveexec_b64 s[44:45], s[2:3]
	s_cbranch_execz .Lmy_cpf_l1
	v_mov_b32_e32 v5, v129
	v_lshl_add_u64 v[0:1], v[6:7], 0, v[4:5]
	v_mov_b32_e32 v44, v216
	v_mov_b32_e32 v45, v217
	v_mov_b32_e32 v46, v218
	v_mov_b32_e32 v47, v219
.Lmy_cpf_l1:
	s_or_b64 exec, exec, s[44:45]
	v_mov_b32_e32 v29, 0
	v_mov_b32_e32 v30, 0
	v_mov_b32_e32 v31, 0
	s_and_saveexec_b64 s[44:45], s[2:3]
	s_cbranch_execz .Lmy_cpf_l2
	v_mov_b32_e32 v5, v129
	v_lshl_add_u64 v[0:1], v[6:7], 0, v[4:5]
	v_add_co_u32_e32 v0, vcc, 0x4000, v0
	s_nop 1
	v_addc_co_u32_e32 v1, vcc, 0, v1, vcc
	v_mov_b32_e32 v28, v220
	v_mov_b32_e32 v29, v221
	v_mov_b32_e32 v30, v222
	v_mov_b32_e32 v31, v223
.Lmy_cpf_l2:
	s_or_b64 exec, exec, s[44:45]
	v_mov_b32_e32 v0, 0
	v_mov_b32_e32 v12, 0
	v_mov_b32_e32 v13, 0
	v_mov_b32_e32 v14, 0
	v_mov_b32_e32 v15, 0
	s_and_saveexec_b64 s[44:45], s[2:3]
	s_cbranch_execz .Lmy_cpf_l3
	v_mov_b32_e32 v5, v129
	v_lshl_add_u64 v[2:3], v[6:7], 0, v[4:5]
	v_add_co_u32_e32 v2, vcc, 0x8000, v2
	s_nop 1
	v_addc_co_u32_e32 v3, vcc, 0, v3, vcc
	v_mov_b32_e32 v12, v224
	v_mov_b32_e32 v13, v225
	v_mov_b32_e32 v14, v226
	v_mov_b32_e32 v15, v227
.Lmy_cpf_l3:
	s_or_b64 exec, exec, s[44:45]
	v_mov_b32_e32 v1, 0
	v_mov_b32_e32 v2, 0
	v_mov_b32_e32 v3, 0
	s_and_saveexec_b64 s[44:45], s[2:3]
	s_cbranch_execz .LBB0_424
	v_mov_b32_e32 v5, v129
	v_lshl_add_u64 v[0:1], v[6:7], 0, v[4:5]
	v_add_co_u32_e32 v0, vcc, 0xc000, v0
	s_nop 1
	v_addc_co_u32_e32 v1, vcc, 0, v1, vcc
	v_mov_b32_e32 v0, v228
	v_mov_b32_e32 v1, v229
	v_mov_b32_e32 v2, v230
	v_mov_b32_e32 v3, v231
	s_branch .LBB0_424

; template <bool OUT>
; DI void s5_item(int wv0, PP p, int item, unsigned char* smem) {
;   const int tid = my_tid(wv0), lane = tid & 63, fr = lane & 15, fq = lane >> 4;
;   const int b = item >> 9, g = (item >> 4) & 31, c8 = item & 15, ch = c8 * 8 + wv0;
;   u16* sBb = (u16*)smem;
;   u16* sCm = sBb + 128 * 16;
;   float* sBU = (float*)(smem + 8192) + wv0 * (16 * 132);
;   u16* sH = (u16*)(smem + 8192 + 8 * 16 * 132 * 4) + wv0 * (16 * 136);
;   *(uint4*)(smem + tid * 16) = *(const uint4*)(p->ws + OFF_S5T + (size_t)g * 8192 + tid * 16);
;   const float2 lb = ((const float2*)(p->ws + OFF_S5L))[g * 64 + lane];
;   const float lbr = lb.x, lbi = lb.y;
;   float2* HL = (float2*)(p->ws + OFF_HLOC) + ((size_t)(b * 128 + ch) * 32 + g) * 64 + lane;
;   float hr = 0.f, hi = 0.f;
;   if (OUT) { const float2 h0 = *HL; hr = h0.x; hi = h0.y; }
;   const u16* U = (const u16*)(p->ws + OFF_U) + ((size_t)(b * S_ + ch * 64)) * 512 + g * 16;
;   u16* YS = (u16*)(p->ws + OFF_YS) + ((size_t)(b * S_ + ch * 64)) * 512 + g * 16;
;   const float dk = p->dsk[g * 16 + fr];
;   const bf16x8 zero8 = {0, 0, 0, 0, 0, 0, 0, 0};
;   bf16x8 uall[4];
;   u16 usk[4][4];
; #pragma unroll
;   for (int sub = 0; sub < 4; ++sub) {
;     uall[sub] = fq < 2 ? *(const bf16x8*)(U + (size_t)(sub * 16 + fr) * 512 + 8 * fq) : zero8;
; DI void phaseC(int wv0, PP p, unsigned char* smem) {
;   for (int id = blockIdx.x; id < 128 + 2048 + 256; id += gridDim.x) {
;     if (id >= 128 + 2048) {
;       const int it = id - (128 + 2048), tns = it >> 7, bg = (it >> 4) & 7, part = it & 15;
;       const int tid = my_tid(wv0);
.LBB0_414:
	s_cmpk_lt_i32 s64, 0x880
	s_mov_b64 s[2:3], -1
	s_cbranch_scc0 .LBB0_458
	s_cmpk_gt_i32 s64, 0x7f
	s_cbranch_scc0 .LBB0_449
	s_cmp_eq_u32 s78, s64
	s_cbranch_scc1 .Lmy_cpf_use
	v_mov_b32_e32 v52, v144
	s_load_dwordx2 s[42:43], s[6:7], 0xc8
	s_add_i32 s2, s64, 0xffffff80
	s_lshr_b32 s66, s2, 9
	s_bfe_u32 s65, s2, 0x50004
	s_lshl_b32 s2, s2, 3
	s_and_b32 s67, s2, 0x78
	s_add_i32 s67, s67, s89
	s_lshl_b32 s2, s65, 13
	s_waitcnt lgkmcnt(0)
	s_add_u32 s2, s42, s2
	v_lshlrev_b32_e32 v4, 4, v52
	v_and_b32_e32 v49, 63, v52
	s_addc_u32 s3, s43, 0
	v_ashrrev_i32_e32 v5, 31, v4
	v_lshl_add_u64 v[0:1], s[2:3], 0, v[4:5]
	v_lshlrev_b32_e32 v48, 3, v49
	v_add_co_u32_e32 v0, vcc, s59, v0
	v_lshl_or_b32 v128, s65, 9, v48
	s_nop 0
	v_addc_co_u32_e32 v1, vcc, 0, v1, vcc
	v_lshl_add_u64 v[6:7], s[42:43], 0, v[128:129]
	v_add_co_u32_e32 v6, vcc, s60, v6
	global_load_dwordx4 v[200:203], v[0:1], off offset:256
	s_nop 0
	v_addc_co_u32_e32 v7, vcc, 0, v7, vcc
	global_load_dwordx2 v[50:51], v[6:7], off offset:256
	s_lshl_b32 s14, s66, 13
	s_lshl_b32 s44, s67, 6
	s_add_i32 s14, s44, s14
	s_lshl_b64 s[44:45], s[14:15], 10
	s_add_u32 s14, s42, s44
	s_addc_u32 s45, s43, s45
	s_lshl_b32 s44, s65, 5
	s_add_u32 s44, s14, s44
	v_and_b32_e32 v53, 15, v52
	v_and_b32_e32 v128, 48, v52
	s_addc_u32 s45, s45, 0
	v_add_u32_e32 v204, 32, v4
	v_lshlrev_b32_e32 v4, 9, v53
	v_lshl_add_u64 v[6:7], s[44:45], 0, v[128:129]
	v_mov_b32_e32 v28, 0
	v_mov_b32_e32 v44, 0
	v_mov_b32_e32 v45, 0
	v_mov_b32_e32 v46, 0
	v_cmp_gt_u32_e64 s[2:3], 32, v49
	v_lshlrev_b32_e32 v4, 1, v4
	v_lshl_add_u64 v[6:7], v[6:7], 0, s[16:17]
	v_mov_b32_e32 v47, 0
	s_and_saveexec_b64 s[44:45], s[2:3]
	s_cbranch_execz .LBB0_418
	v_mov_b32_e32 v5, v129
	v_lshl_add_u64 v[0:1], v[6:7], 0, v[4:5]
	global_load_dwordx4 v[44:47], v[0:1], off

; DI f32x4 mfma16(bf16x8 a, bf16x8 b, f32x4 c) { return __builtin_amdgcn_mfma_f32_16x16x32_bf16(a, b, c, 0, 0, 0); }
; template <bool OUT>
; DI void s5_item(int wv0, PP p, int item, unsigned char* smem) {
;     ...
;   __syncthreads();
;   bf16x8 bb[8], cf[4];
; #pragma unroll
;   for (int nt = 0; nt < 8; ++nt) bb[nt] = fq < 2 ? *(const bf16x8*)(sBb + (16 * nt + fr) * 16 + 8 * fq) : zero8;
;   if (OUT) {
; #pragma unroll
;     for (int ks = 0; ks < 4; ++ks) cf[ks] = *(const bf16x8*)(sCm + fr * 128 + 32 * ks + 8 * fq);
;   }
; #pragma unroll
;   for (int sub = 0; sub < 4; ++sub) {
;     const bf16x8 ua = uall[sub];
; #pragma unroll
;     for (int nt = 0; nt < 8; ++nt) {
;       const f32x4 a = mfma16(ua, bb[nt], f32x4{0.f, 0.f, 0.f, 0.f});
; #pragma unroll
;       for (int j = 0; j < 4; ++j) sBU[(4 * fq + j) * 132 + 16 * nt + fr] = a[j];
;     }
;     __syncthreads();
.LBB0_424:
	s_or_b64 exec, exec, s[44:45]
	v_lshl_add_u32 v5, v53, 5, 32
	v_mov_b32_e32 v4, 0
	v_add_u32_e32 v54, v5, v128
	v_mov_b32_e32 v8, 0
	v_mov_b32_e32 v9, 0
	v_mov_b32_e32 v10, 0
	v_mov_b32_e32 v11, 0
	s_waitcnt vmcnt(4)
	ds_write_b128 v204, v[200:203]
	s_waitcnt lgkmcnt(0)
	s_barrier
	s_and_saveexec_b64 s[44:45], s[2:3]
	ds_read_b128 v[8:11], v54
	s_or_b64 exec, exec, s[44:45]
	v_mov_b32_e32 v5, 0
	v_mov_b32_e32 v6, 0
	v_mov_b32_e32 v7, 0
	s_and_saveexec_b64 s[44:45], s[2:3]
	ds_read_b128 v[4:7], v54 offset:512
	s_or_b64 exec, exec, s[44:45]
	v_mov_b32_e32 v16, 0
	v_mov_b32_e32 v20, 0
	v_mov_b32_e32 v21, 0
	v_mov_b32_e32 v22, 0
	v_mov_b32_e32 v23, 0
	s_and_saveexec_b64 s[44:45], s[2:3]
	ds_read_b128 v[20:23], v54 offset:1024
	s_or_b64 exec, exec, s[44:45]
	v_mov_b32_e32 v17, 0
	v_mov_b32_e32 v18, 0
	v_mov_b32_e32 v19, 0
	s_and_saveexec_b64 s[44:45], s[2:3]
	ds_read_b128 v[16:19], v54 offset:1536
	s_or_b64 exec, exec, s[44:45]
	v_mov_b32_e32 v24, 0
	v_mov_b32_e32 v32, 0
	v_mov_b32_e32 v33, 0
	v_mov_b32_e32 v34, 0
	v_mov_b32_e32 v35, 0
	s_and_saveexec_b64 s[44:45], s[2:3]
	ds_read_b128 v[32:35], v54 offset:2048
	s_or_b64 exec, exec, s[44:45]
	v_mov_b32_e32 v25, 0
	v_mov_b32_e32 v26, 0
	v_mov_b32_e32 v27, 0
	s_and_saveexec_b64 s[44:45], s[2:3]
	ds_read_b128 v[24:27], v54 offset:2560
	s_or_b64 exec, exec, s[44:45]
	v_mov_b32_e32 v36, 0
	v_mov_b32_e32 v40, 0
	v_mov_b32_e32 v41, 0
	v_mov_b32_e32 v42, 0
	v_mov_b32_e32 v43, 0
	s_and_saveexec_b64 s[44:45], s[2:3]
	ds_read_b128 v[40:43], v54 offset:3072
	s_or_b64 exec, exec, s[44:45]
	s_mov_b32 s14, 0
	v_mov_b32_e32 v37, 0
	v_mov_b32_e32 v38, 0
	v_mov_b32_e32 v39, 0
	s_and_saveexec_b64 s[44:45], s[2:3]
	ds_read_b128 v[36:39], v54 offset:3584
	s_or_b64 exec, exec, s[44:45]
	s_waitcnt vmcnt(0) lgkmcnt(0)
	s_load_dword s79, s[12:13], 0x0
	s_load_dwordx2 s[80:81], s[6:7], 0xc8
	s_mov_b32 s78, -1
	s_waitcnt lgkmcnt(0)
	s_add_i32 s79, s79, s64
	s_cmpk_lt_i32 s79, 0x880
	s_cbranch_scc0 .Lmy_cpf_none
	s_mov_b32 s78, s79
	s_add_i32 s83, s79, 0xffffff80
	s_lshr_b32 s84, s83, 9
	s_bfe_u32 s85, s83, 0x50004
	s_lshl_b32 s83, s83, 3
	s_and_b32 s83, s83, 0x78
	s_add_i32 s83, s83, s89
	s_lshl_b32 s86, s85, 13
	s_add_u32 s86, s80, s86
	s_addc_u32 s87, s81, 0
	v_lshlrev_b32_e32 v232, 4, v144
	v_ashrrev_i32_e32 v233, 31, v232
	v_lshl_add_u64 v[234:235], s[86:87], 0, v[232:233]
	v_add_co_u32_e32 v234, vcc, s59, v234
	s_nop 1
	v_addc_co_u32_e32 v235, vcc, 0, v235, vcc
	global_load_dwordx4 v[210:213], v[234:235], off offset:256
	v_and_b32_e32 v236, 63, v144
	v_lshlrev_b32_e32 v237, 3, v236
	v_lshl_or_b32 v238, s85, 9, v237
	v_mov_b32_e32 v239, 0
	v_lshl_add_u64 v[240:241], s[80:81], 0, v[238:239]
	v_add_co_u32_e32 v240, vcc, s60, v240
	s_nop 1
	v_addc_co_u32_e32 v241, vcc, 0, v241, vcc
	global_load_dwordx2 v[214:215], v[240:241], off offset:256
	s_lshl_b32 s86, s84, 13
	s_lshl_b32 s87, s83, 6
	s_add_i32 s86, s87, s86
	s_mov_b32 s87, 0
	s_lshl_b64 s[86:87], s[86:87], 10
	s_add_u32 s86, s80, s86
	s_addc_u32 s87, s81, s87
	s_lshl_b32 s88, s85, 5
	s_add_u32 s86, s86, s88
	s_addc_u32 s87, s87, 0
	v_and_b32_e32 v238, 48, v144
	v_lshl_add_u64 v[240:241], s[86:87], 0, v[238:239]
	v_lshl_add_u64 v[240:241], v[240:241], 0, s[16:17]
	v_and_b32_e32 v242, 15, v144
	v_lshlrev_b32_e32 v242, 10, v242
	v_mov_b32_e32 v243, 0
	v_lshl_add_u64 v[240:241], v[240:241], 0, v[242:243]
	v_cmp_gt_u32_e64 s[86:87], 32, v236
	s_and_saveexec_b64 s[86:87], s[86:87]
	global_load_dwordx4 v[216:219], v[240:241], off
	v_add_co_u32_e32 v244, vcc, 0x4000, v240
	s_nop 1
	v_addc_co_u32_e32 v245, vcc, 0, v241, vcc
	global_load_dwordx4 v[220:223], v[244:245], off
	v_add_co_u32_e32 v244, vcc, 0x8000, v240
	s_nop 1
	v_addc_co_u32_e32 v245, vcc, 0, v241, vcc
	global_load_dwordx4 v[224:227], v[244:245], off
	v_add_co_u32_e32 v244, vcc, 0xc000, v240
	s_nop 1
	v_addc_co_u32_e32 v245, vcc, 0, v241, vcc
	global_load_dwordx4 v[228:231], v[244:245], off
	s_or_b64 exec, exec, s[86:87]
.Lmy_cpf_none:
	v_mfma_f32_16x16x32_bf16 v[54:57], v[44:47], v[8:11], 0
	v_bfe_u32 v52, v52, 4, 2
	v_lshlrev_b32_e32 v53, 2, v53
	v_mul_u32_u24_e32 v52, 0x840, v52
	v_mfma_f32_16x16x32_bf16 v[58:61], v[44:47], v[4:7], 0
	v_add3_u32 v52, s0, v53, v52
	v_add_u32_e32 v53, 0x2000, v52
	v_lshl_add_u32 v49, v49, 2, s58
	v_mfma_f32_16x16x32_bf16 v[62:65], v[44:47], v[20:23], 0
	v_mfma_f32_16x16x32_bf16 v[66:69], v[44:47], v[16:19], 0
	s_nop 2
	ds_write2_b32 v53, v54, v58 offset1:16
	v_add_u32_e32 v54, 0x2400, v52
	ds_write2_b32 v53, v55, v59 offset0:132 offset1:148
	ds_write2_b32 v54, v56, v60 offset0:8 offset1:24
	v_mfma_f32_16x16x32_bf16 v[70:73], v[44:47], v[32:35], 0
	ds_write2_b32 v54, v57, v61 offset0:140 offset1:156
	ds_write2_b32 v53, v62, v66 offset0:32 offset1:48
	ds_write2_b32 v53, v63, v67 offset0:164 offset1:180
	v_mov_b32_e32 v52, 0
	v_mfma_f32_16x16x32_bf16 v[56:59], v[44:47], v[24:27], 0
	ds_write2_b32 v54, v64, v68 offset0:40 offset1:56
	ds_write2_b32 v54, v65, v69 offset0:172 offset1:188
	s_nop 5
	ds_write2_b32 v53, v70, v56 offset0:64 offset1:80
	ds_write2_b32 v53, v71, v57 offset0:196 offset1:212
	ds_write2_b32 v54, v72, v58 offset0:72 offset1:88
	ds_write2_b32 v54, v73, v59 offset0:204 offset1:220
	v_mfma_f32_16x16x32_bf16 v[60:63], v[44:47], v[40:43], 0
	v_mfma_f32_16x16x32_bf16 v[44:47], v[44:47], v[36:39], 0
	s_nop 7
	ds_write2_b32 v53, v60, v44 offset0:96 offset1:112
	ds_write2_b32 v53, v61, v45 offset0:228 offset1:244
	ds_write2_b32 v54, v62, v46 offset0:104 offset1:120
	ds_write2_b32 v54, v63, v47 offset0:236 offset1:252
	v_pk_mov_b32 v[44:45], v[50:51], v[50:51] op_sel:[1,0]
	v_mov_b32_e32 v46, 0
	s_waitcnt lgkmcnt(0)
	s_barrier
